# v27: v26 + kind-0 in-proj tiles also take row scales / first-half maxima from the loads issued at the top of the K loop (10 of 14 tiles now start their epilogue without a vmcnt(0))
# baseline (speedup 1.0000x reference)
;     template <int KIND>
;     __device__ __forceinline__ void run(const f32x4 (&acc)[2][2][4][2], const Unit& u, int wr, int wc, int fr, int fq) const {
;         const int row0 = u.pm * BM + wr * 64 + fr, col0 = u.pn * BM + wc * 32 + 8 * fq;
;         const float sa_lo = sa[u.pm * BM + wr * 64 + fr + 16 * fq], sa_hi = sa[u.pm * BM + HALF + wr * 64 + fr + 16 * fq];
; #pragma unroll
;         for (int bj = 0; bj < 2; ++bj) {
;             f32x2_t sc2[4], aux2[4];
; #pragma unroll
;             for (int j = 0; j < 4; ++j) {
;                 const float k0 = (KIND == 4) ? (0.125f * LOG2E / 127.0f) : (1.0f / 127.0f);
;                 sc2[j] = (f32x2_t){wmax[col0 + bj * HALF + 2 * j] * k0, wmax[col0 + bj * HALF + 2 * j + 1] * k0};
;                 if (KIND == 1) aux2[j] = (f32x2_t){lb[col0 - C_HG + bj * HALF + 2 * j], lb[col0 - C_HG + bj * HALF + 2 * j + 1]};
;                 else if (KIND == 3) aux2[j] = (f32x2_t){gain[col0 - C_HGATE + bj * HALF + 2 * j], gain[col0 - C_HGATE + bj * HALF + 2 * j + 1]};
;                 else aux2[j] = (f32x2_t){0.f, 0.f};
;             }
; #pragma unroll
;             for (int ai = 0; ai < 2; ++ai)
; #pragma unroll
;                 for (int m = 0; m < 4; ++m) { const int row = row0 + ai * HALF + m * 16; const float a = __shfl(ai ? sa_hi : sa_lo, 16 * m + fr);
;                     const f32x4 f0 = __builtin_convertvector(__builtin_bit_cast(i32x4, acc[ai][bj][m][0]), f32x4), f1 = __builtin_convertvector(__builtin_bit_cast(i32x4, acc[ai][bj][m][1]), f32x4);
;                     f32x2_t v[4] = {(f32x2_t){f0[0], f0[1]}, (f32x2_t){f0[2], f0[3]}, (f32x2_t){f1[0], f1[1]}, (f32x2_t){f1[2], f1[3]}};
; #pragma unroll
;                     for (int j = 0; j < 4; ++j) {
;                         v[j] = v[j] * (sc2[j] * (f32x2_t){a, a});
;                         if (KIND == 0 || KIND == 1 || KIND == 3) {
;                             const f32x2_t e = v[j] * (f32x2_t){-LOG2E, -LOG2E};
;                             const f32x2_t dn = (f32x2_t){__builtin_amdgcn_exp2f(e[0]), __builtin_amdgcn_exp2f(e[1])} + (f32x2_t){1.0f, 1.0f};
;                             const f32x2_t sg = (f32x2_t){fast_rcp(dn[0]), fast_rcp(dn[1])};
;                             if (KIND == 0) v[j] = v[j] * sg;
;                             else if (KIND == 3) v[j] = (v[j] * sg) * aux2[j];
.LBB0_212:
	s_and_b64 vcc, exec, s[0:1]
	s_cbranch_vccz .LBB0_214
	s_lshl_b32 s0, s90, 8
	v_add_u32_e32 v133, s0, v212
	v_or_b32_e32 v134, v133, v214
	v_ashrrev_i32_e32 v135, 31, v134
	v_lshl_add_u64 v[134:135], v[134:135], 2, s[46:47]
	v_mov_b32_e32 v154, v209
	v_add_u32_e32 v134, s0, v215
	v_ashrrev_i32_e32 v135, 31, v134
	v_lshl_add_u64 v[134:135], v[134:135], 2, s[46:47]
	v_mov_b32_e32 v147, v67
	v_mov_b32_e32 v152, v208
	v_lshl_add_u64 v[134:135], v[146:147], 2, s[48:49]
	v_mov_b32_e32 v156, v240
	v_mov_b32_e32 v157, v241
	v_mov_b32_e32 v158, v242
	v_mov_b32_e32 v159, v243
	v_mov_b32_e32 v136, v236
	v_mov_b32_e32 v137, v237
	v_mov_b32_e32 v138, v238
	v_mov_b32_e32 v139, v239
	global_load_dwordx4 v[236:239], v[134:135], off offset:528
	global_load_dwordx4 v[240:243], v[134:135], off offset:512
	v_lshlrev_b32_e32 v153, 2, v233
	v_cvt_f32_i32_e32 v129, v129
	v_cvt_f32_i32_e32 v128, v128
	s_mov_b32 s2, 0x3c010204
	s_mov_b32 s6, 0xbfb8aa3b
	v_cvt_f32_i32_e32 v131, v131
	v_cvt_f32_i32_e32 v130, v130
	v_cvt_f32_i32_e32 v125, v125
	v_cvt_f32_i32_e32 v124, v124
	v_cvt_f32_i32_e32 v127, v127
	v_cvt_f32_i32_e32 v126, v126
	v_lshlrev_b32_e32 v66, 1, v146
	v_cvt_f32_i32_e32 v121, v121
	v_cvt_f32_i32_e32 v120, v120
	v_cvt_f32_i32_e32 v123, v123
	v_cvt_f32_i32_e32 v122, v122
	v_cvt_f32_i32_e32 v119, v119
	v_cvt_f32_i32_e32 v118, v118
	v_cvt_f32_i32_e32 v113, v113
	v_cvt_f32_i32_e32 v112, v112
	v_cvt_f32_i32_e32 v115, v115
	v_cvt_f32_i32_e32 v114, v114
	v_cvt_f32_i32_e32 v109, v109
	v_cvt_f32_i32_e32 v108, v108
	v_cvt_f32_i32_e32 v111, v111
	v_cvt_f32_i32_e32 v110, v110
	v_cvt_f32_i32_e32 v105, v105
	v_cvt_f32_i32_e32 v104, v104
	v_cvt_f32_i32_e32 v107, v107
	v_cvt_f32_i32_e32 v106, v106
	v_cvt_f32_i32_e32 v101, v101
	v_cvt_f32_i32_e32 v100, v100
	v_cvt_f32_i32_e32 v103, v103
	v_cvt_f32_i32_e32 v102, v102
	v_cvt_f32_i32_e32 v97, v97
	v_cvt_f32_i32_e32 v96, v96
	v_cvt_f32_i32_e32 v99, v99
	v_cvt_f32_i32_e32 v98, v98
	v_cvt_f32_i32_e32 v93, v93
	v_cvt_f32_i32_e32 v92, v92
	v_cvt_f32_i32_e32 v95, v95
	v_cvt_f32_i32_e32 v94, v94
	v_cvt_f32_i32_e32 v89, v89
	v_cvt_f32_i32_e32 v88, v88
	v_cvt_f32_i32_e32 v91, v91
	v_cvt_f32_i32_e32 v90, v90
	v_cvt_f32_i32_e32 v85, v85
	v_cvt_f32_i32_e32 v84, v84
	v_cvt_f32_i32_e32 v87, v87
	v_cvt_f32_i32_e32 v86, v86
	v_cvt_f32_i32_e32 v81, v81
	v_cvt_f32_i32_e32 v80, v80
	v_cvt_f32_i32_e32 v83, v83
	v_cvt_f32_i32_e32 v82, v82
	v_cvt_f32_i32_e32 v77, v77
	v_cvt_f32_i32_e32 v76, v76
	v_cvt_f32_i32_e32 v79, v79
	v_cvt_f32_i32_e32 v78, v78
	v_cvt_f32_i32_e32 v73, v73
	v_cvt_f32_i32_e32 v72, v72
	v_cvt_f32_i32_e32 v75, v75
	v_cvt_f32_i32_e32 v74, v74
	v_cvt_f32_i32_e32 v69, v69
	v_cvt_f32_i32_e32 v68, v68
	v_cvt_f32_i32_e32 v71, v71
	v_cvt_f32_i32_e32 v70, v70
	v_cvt_f32_i32_e32 v63, v63
	v_cvt_f32_i32_e32 v62, v62
	v_cvt_f32_i32_e32 v65, v65
	v_cvt_f32_i32_e32 v64, v64
	v_cvt_f32_i32_e32 v59, v59
	v_cvt_f32_i32_e32 v58, v58
	ds_bpermute_b32 v132, v153, v154
	v_cvt_f32_i32_e32 v61, v61
	v_cvt_f32_i32_e32 v60, v60
	v_cvt_f32_i32_e32 v55, v55
	v_cvt_f32_i32_e32 v54, v54
	v_cvt_f32_i32_e32 v57, v57
	v_cvt_f32_i32_e32 v56, v56
	v_pk_mul_f32 v[150:151], v[136:137], s[2:3] op_sel_hi:[1,0]
	v_pk_mul_f32 v[148:149], v[138:139], s[2:3] op_sel_hi:[1,0]
	v_pk_mul_f32 v[138:139], v[156:157], s[2:3] op_sel_hi:[1,0]
	s_waitcnt lgkmcnt(0)
	v_pk_mul_f32 v[156:157], v[150:151], v[132:133] op_sel_hi:[1,0]
	v_pk_mul_f32 v[136:137], v[158:159], s[2:3] op_sel_hi:[1,0]
	v_pk_mul_f32 v[128:129], v[128:129], v[156:157]
	v_cvt_f32_i32_e32 v51, v51
	v_pk_mul_f32 v[156:157], v[128:129], s[6:7] op_sel_hi:[1,0]
	v_cvt_f32_i32_e32 v50, v50
	v_exp_f32_e32 v156, v156
	v_exp_f32_e32 v157, v157
	v_cvt_f32_i32_e32 v53, v53
	v_cvt_f32_i32_e32 v52, v52
	v_cvt_f32_i32_e32 v47, v47
	v_pk_add_f32 v[156:157], v[156:157], 1.0 op_sel_hi:[1,0]
	v_cvt_f32_i32_e32 v46, v46
	v_rcp_f32_e32 v156, v156
	v_rcp_f32_e32 v157, v157
	v_cvt_f32_i32_e32 v49, v49
	v_cvt_f32_i32_e32 v48, v48
	v_cvt_f32_i32_e32 v43, v43
	v_pk_mul_f32 v[128:129], v[128:129], v[156:157]
	v_pk_mul_f32 v[156:157], v[148:149], v[132:133] op_sel_hi:[1,0]
	v_cvt_f32_i32_e32 v42, v42
	v_pk_mul_f32 v[130:131], v[130:131], v[156:157]
	v_cvt_f32_i32_e32 v45, v45
	v_pk_mul_f32 v[156:157], v[130:131], s[6:7] op_sel_hi:[1,0]
	v_cvt_f32_i32_e32 v44, v44
	v_exp_f32_e32 v156, v156
	v_exp_f32_e32 v157, v157
	v_cvt_f32_i32_e32 v39, v39
	v_cvt_f32_i32_e32 v38, v38
	v_cvt_f32_i32_e32 v41, v41
	v_pk_add_f32 v[156:157], v[156:157], 1.0 op_sel_hi:[1,0]
	v_cvt_f32_i32_e32 v40, v40
	v_rcp_f32_e32 v156, v156
	v_rcp_f32_e32 v157, v157
	v_cvt_f32_i32_e32 v35, v35
	v_cvt_f32_i32_e32 v34, v34
	v_cvt_f32_i32_e32 v37, v37
	v_pk_mul_f32 v[130:131], v[130:131], v[156:157]
	v_pk_mul_f32 v[156:157], v[138:139], v[132:133] op_sel_hi:[1,0]
	v_cvt_f32_i32_e32 v36, v36
	v_pk_mul_f32 v[124:125], v[124:125], v[156:157]
	v_cvt_f32_i32_e32 v31, v31
	v_pk_mul_f32 v[156:157], v[124:125], s[6:7] op_sel_hi:[1,0]
	v_cvt_f32_i32_e32 v30, v30
	v_exp_f32_e32 v156, v156
	v_exp_f32_e32 v157, v157
	v_cvt_f32_i32_e32 v33, v33
	v_cvt_f32_i32_e32 v32, v32
	v_cvt_f32_i32_e32 v27, v27
	v_pk_add_f32 v[156:157], v[156:157], 1.0 op_sel_hi:[1,0]
	v_cvt_f32_i32_e32 v26, v26
	v_rcp_f32_e32 v156, v156
	v_rcp_f32_e32 v157, v157
	v_cvt_f32_i32_e32 v29, v29
	v_cvt_f32_i32_e32 v28, v28
	v_cvt_f32_i32_e32 v23, v23
	v_pk_mul_f32 v[124:125], v[124:125], v[156:157]
	v_pk_mul_f32 v[156:157], v[136:137], v[132:133] op_sel_hi:[1,0]
	v_cvt_pk_bf16_f32 v158, v124, v125
	v_pk_mul_f32 v[126:127], v[126:127], v[156:157]
	v_cvt_f32_i32_e32 v22, v22
	v_pk_mul_f32 v[156:157], v[126:127], s[6:7] op_sel_hi:[1,0]
	v_cvt_f32_i32_e32 v25, v25
	v_exp_f32_e32 v156, v156
	v_exp_f32_e32 v157, v157
	v_cvt_f32_i32_e32 v24, v24
	v_cvt_f32_i32_e32 v19, v19
	v_cvt_f32_i32_e32 v18, v18
	v_pk_add_f32 v[156:157], v[156:157], 1.0 op_sel_hi:[1,0]
	v_cvt_f32_i32_e32 v21, v21
	v_rcp_f32_e32 v156, v156
	v_rcp_f32_e32 v157, v157
	v_cvt_f32_i32_e32 v20, v20
	v_cvt_f32_i32_e32 v15, v15
	v_cvt_f32_i32_e32 v14, v14
	v_pk_mul_f32 v[126:127], v[126:127], v[156:157]
	v_cvt_pk_bf16_f32 v156, v128, v129
	v_mov_b64_e32 v[128:129], s[14:15]
	v_mad_i64_i32 v[124:125], s[0:1], v133, s81, v[128:129]
	v_cvt_pk_bf16_f32 v159, v126, v127
	v_lshl_add_u64 v[126:127], v[124:125], 0, v[66:67]
	ds_bpermute_b32 v124, v153, v154 offset:64
	v_cvt_pk_bf16_f32 v157, v130, v131
	v_cvt_f32_i32_e32 v131, v117
	v_cvt_f32_i32_e32 v130, v116
	global_store_dwordx4 v[126:127], v[156:159], off
	s_waitcnt lgkmcnt(0)
; __device__ __forceinline__ unsigned cvt_pk_bf16(float lo, float hi) { f32x2_t v = {lo, hi}; bf16x2_t b = __builtin_convertvector(v, bf16x2_t); return __builtin_bit_cast(unsigned, b); }
; __device__ __forceinline__ float fast_rcp(float x) { return __builtin_amdgcn_rcpf(x); }
;     template <int KIND>
;     __device__ __forceinline__ void run(const f32x4 (&acc)[2][2][4][2], const Unit& u, int wr, int wc, int fr, int fq) const {
;     ...
;                 for (int m = 0; m < 4; ++m) { const int row = row0 + ai * HALF + m * 16; const float a = __shfl(ai ? sa_hi : sa_lo, 16 * m + fr);
;                     const f32x4 f0 = __builtin_convertvector(__builtin_bit_cast(i32x4, acc[ai][bj][m][0]), f32x4), f1 = __builtin_convertvector(__builtin_bit_cast(i32x4, acc[ai][bj][m][1]), f32x4);
;                     f32x2_t v[4] = {(f32x2_t){f0[0], f0[1]}, (f32x2_t){f0[2], f0[3]}, (f32x2_t){f1[0], f1[1]}, (f32x2_t){f1[2], f1[3]}};
; #pragma unroll
;                     for (int j = 0; j < 4; ++j) {
;                         v[j] = v[j] * (sc2[j] * (f32x2_t){a, a});
;                         if (KIND == 0 || KIND == 1 || KIND == 3) {
;                             const f32x2_t e = v[j] * (f32x2_t){-LOG2E, -LOG2E};
;                             const f32x2_t dn = (f32x2_t){__builtin_amdgcn_exp2f(e[0]), __builtin_amdgcn_exp2f(e[1])} + (f32x2_t){1.0f, 1.0f};
;                             const f32x2_t sg = (f32x2_t){fast_rcp(dn[0]), fast_rcp(dn[1])};
;                             if (KIND == 0) v[j] = v[j] * sg;
;                             else if (KIND == 3) v[j] = (v[j] * sg) * aux2[j];
;                             else { const f32x2_t f = __builtin_elementwise_fma((f32x2_t){1.0f, 1.0f} - aux2[j], sg, aux2[j]);
;                                 v[j] = (f32x2_t){fmaxf(__logf(f[0]), -60.0f), fmaxf(__logf(f[1]), -60.0f)}; }
;                         }
;                     }
;                     u32x4 w; w.x = cvt_pk_bf16(v[0][0], v[0][1]); w.y = cvt_pk_bf16(v[1][0], v[1][1]); w.z = cvt_pk_bf16(v[2][0], v[2][1]); w.w = cvt_pk_bf16(v[3][0], v[3][1]);
;                     *(u32x4*)(O + (size_t)row * NPROJ + col0 + bj * HALF) = w; }
	v_pk_mul_f32 v[116:117], v[150:151], v[124:125] op_sel_hi:[1,0]
	v_cvt_f32_i32_e32 v17, v17
	v_pk_mul_f32 v[116:117], v[120:121], v[116:117]
	v_cvt_f32_i32_e32 v16, v16
	v_pk_mul_f32 v[120:121], v[116:117], s[6:7] op_sel_hi:[1,0]
	v_cvt_f32_i32_e32 v11, v11
	v_exp_f32_e32 v120, v120
	v_exp_f32_e32 v121, v121
	v_cvt_f32_i32_e32 v10, v10
	v_cvt_f32_i32_e32 v13, v13
	v_cvt_f32_i32_e32 v12, v12
	v_pk_add_f32 v[120:121], v[120:121], 1.0 op_sel_hi:[1,0]
	v_cvt_f32_i32_e32 v7, v7
	v_rcp_f32_e32 v120, v120
	v_rcp_f32_e32 v121, v121
	v_cvt_f32_i32_e32 v6, v6
	v_cvt_f32_i32_e32 v9, v9
	v_cvt_f32_i32_e32 v8, v8
	v_pk_mul_f32 v[116:117], v[116:117], v[120:121]
	v_pk_mul_f32 v[120:121], v[148:149], v[124:125] op_sel_hi:[1,0]
	v_cvt_pk_bf16_f32 v156, v116, v117
	v_pk_mul_f32 v[120:121], v[122:123], v[120:121]
	v_cvt_f32_i32_e32 v3, v3
	v_pk_mul_f32 v[122:123], v[120:121], s[6:7] op_sel_hi:[1,0]
	v_cvt_f32_i32_e32 v2, v2
	v_exp_f32_e32 v122, v122
	v_exp_f32_e32 v123, v123
	v_cvt_f32_i32_e32 v5, v5
	v_cvt_f32_i32_e32 v4, v4
	v_pk_add_f32 v[122:123], v[122:123], 1.0 op_sel_hi:[1,0]
	s_nop 0
	v_rcp_f32_e32 v122, v122
	v_rcp_f32_e32 v123, v123
	s_nop 0
	v_pk_mul_f32 v[120:121], v[120:121], v[122:123]
	v_pk_mul_f32 v[122:123], v[138:139], v[124:125] op_sel_hi:[1,0]
	v_cvt_pk_bf16_f32 v157, v120, v121
	v_pk_mul_f32 v[122:123], v[130:131], v[122:123]
	s_nop 0
	v_pk_mul_f32 v[130:131], v[122:123], s[6:7] op_sel_hi:[1,0]
	s_nop 0
	v_exp_f32_e32 v130, v130
	v_exp_f32_e32 v131, v131
	s_nop 0
	v_pk_add_f32 v[130:131], v[130:131], 1.0 op_sel_hi:[1,0]
	s_nop 0
	v_rcp_f32_e32 v130, v130
	v_rcp_f32_e32 v131, v131
	s_nop 0
	v_pk_mul_f32 v[122:123], v[122:123], v[130:131]
	v_pk_mul_f32 v[130:131], v[136:137], v[124:125] op_sel_hi:[1,0]
	v_or_b32_e32 v125, 16, v133
	v_pk_mul_f32 v[118:119], v[118:119], v[130:131]
	v_mad_i64_i32 v[116:117], s[0:1], v125, s81, v[128:129]
	v_pk_mul_f32 v[130:131], v[118:119], s[6:7] op_sel_hi:[1,0]
	v_cvt_pk_bf16_f32 v158, v122, v123
	v_exp_f32_e32 v130, v130
	v_exp_f32_e32 v131, v131
	s_nop 0
	v_pk_add_f32 v[130:131], v[130:131], 1.0 op_sel_hi:[1,0]
	s_nop 0
	v_rcp_f32_e32 v130, v130
	v_rcp_f32_e32 v131, v131
	s_nop 0
	v_pk_mul_f32 v[118:119], v[118:119], v[130:131]
	s_nop 0
	v_cvt_pk_bf16_f32 v159, v118, v119
	v_lshl_add_u64 v[118:119], v[116:117], 0, v[66:67]
	ds_bpermute_b32 v116, v153, v154 offset:128
	global_store_dwordx4 v[118:119], v[156:159], off
	s_waitcnt lgkmcnt(0)
	v_pk_mul_f32 v[120:121], v[150:151], v[116:117] op_sel_hi:[1,0]
	s_nop 0
	v_pk_mul_f32 v[112:113], v[112:113], v[120:121]
	s_nop 0
	v_pk_mul_f32 v[120:121], v[112:113], s[6:7] op_sel_hi:[1,0]
	s_nop 0
	v_exp_f32_e32 v120, v120
	v_exp_f32_e32 v121, v121
	s_nop 0
	v_pk_add_f32 v[120:121], v[120:121], 1.0 op_sel_hi:[1,0]
	s_nop 0
	v_rcp_f32_e32 v120, v120
	v_rcp_f32_e32 v121, v121
	s_nop 0
	v_pk_mul_f32 v[112:113], v[112:113], v[120:121]
	v_pk_mul_f32 v[120:121], v[148:149], v[116:117] op_sel_hi:[1,0]
	v_cvt_pk_bf16_f32 v112, v112, v113
	v_pk_mul_f32 v[114:115], v[114:115], v[120:121]
	s_nop 0
	v_pk_mul_f32 v[120:121], v[114:115], s[6:7] op_sel_hi:[1,0]
	s_nop 0
	v_exp_f32_e32 v120, v120
	v_exp_f32_e32 v121, v121
	s_nop 0
	v_pk_add_f32 v[120:121], v[120:121], 1.0 op_sel_hi:[1,0]
	s_nop 0
	v_rcp_f32_e32 v120, v120
	v_rcp_f32_e32 v121, v121
	s_nop 0
	v_pk_mul_f32 v[114:115], v[114:115], v[120:121]
	v_pk_mul_f32 v[120:121], v[138:139], v[116:117] op_sel_hi:[1,0]
	v_cvt_pk_bf16_f32 v113, v114, v115
	v_pk_mul_f32 v[108:109], v[108:109], v[120:121]
	s_nop 0
	v_pk_mul_f32 v[120:121], v[108:109], s[6:7] op_sel_hi:[1,0]
	s_nop 0
	v_exp_f32_e32 v120, v120
	v_exp_f32_e32 v121, v121
	s_nop 0
	v_pk_add_f32 v[120:121], v[120:121], 1.0 op_sel_hi:[1,0]
	s_nop 0
	v_rcp_f32_e32 v120, v120
	v_rcp_f32_e32 v121, v121
	s_nop 0
	v_pk_mul_f32 v[108:109], v[108:109], v[120:121]
	v_pk_mul_f32 v[120:121], v[136:137], v[116:117] op_sel_hi:[1,0]
	v_or_b32_e32 v117, 32, v133
	v_pk_mul_f32 v[110:111], v[110:111], v[120:121]
	v_cvt_pk_bf16_f32 v114, v108, v109
	v_pk_mul_f32 v[120:121], v[110:111], s[6:7] op_sel_hi:[1,0]
	v_mad_i64_i32 v[108:109], s[0:1], v117, s81, v[128:129]
	v_exp_f32_e32 v120, v120
	v_exp_f32_e32 v121, v121
	s_nop 0
	v_pk_add_f32 v[120:121], v[120:121], 1.0 op_sel_hi:[1,0]
	s_nop 0
	v_rcp_f32_e32 v120, v120
	v_rcp_f32_e32 v121, v121
	s_nop 0
	v_pk_mul_f32 v[110:111], v[110:111], v[120:121]
	s_nop 0
	v_cvt_pk_bf16_f32 v115, v110, v111
	v_lshl_add_u64 v[110:111], v[108:109], 0, v[66:67]
	ds_bpermute_b32 v108, v153, v154 offset:192
	global_store_dwordx4 v[110:111], v[112:115], off
	s_waitcnt lgkmcnt(0)
	s_nop 0
	v_pk_mul_f32 v[112:113], v[150:151], v[108:109] op_sel_hi:[1,0]
	s_nop 0
	v_pk_mul_f32 v[104:105], v[104:105], v[112:113]
	s_nop 0
	v_pk_mul_f32 v[112:113], v[104:105], s[6:7] op_sel_hi:[1,0]
	s_nop 0
	v_exp_f32_e32 v112, v112
	v_exp_f32_e32 v113, v113
	s_nop 0
	v_pk_add_f32 v[112:113], v[112:113], 1.0 op_sel_hi:[1,0]
	s_nop 0
	v_rcp_f32_e32 v112, v112
	v_rcp_f32_e32 v113, v113
	s_nop 0
	v_pk_mul_f32 v[104:105], v[104:105], v[112:113]
	v_pk_mul_f32 v[112:113], v[148:149], v[108:109] op_sel_hi:[1,0]
	v_cvt_pk_bf16_f32 v104, v104, v105
	v_pk_mul_f32 v[106:107], v[106:107], v[112:113]
	s_nop 0
	v_pk_mul_f32 v[112:113], v[106:107], s[6:7] op_sel_hi:[1,0]
	s_nop 0
	v_exp_f32_e32 v112, v112
	v_exp_f32_e32 v113, v113
	s_nop 0
	v_pk_add_f32 v[112:113], v[112:113], 1.0 op_sel_hi:[1,0]
	s_nop 0
	v_rcp_f32_e32 v112, v112
	v_rcp_f32_e32 v113, v113
	s_nop 0
	v_pk_mul_f32 v[106:107], v[106:107], v[112:113]
	v_pk_mul_f32 v[112:113], v[138:139], v[108:109] op_sel_hi:[1,0]
	v_cvt_pk_bf16_f32 v105, v106, v107
	v_pk_mul_f32 v[100:101], v[100:101], v[112:113]
	s_nop 0
	v_pk_mul_f32 v[112:113], v[100:101], s[6:7] op_sel_hi:[1,0]
	s_nop 0
	v_exp_f32_e32 v112, v112
	v_exp_f32_e32 v113, v113
	s_nop 0
	v_pk_add_f32 v[112:113], v[112:113], 1.0 op_sel_hi:[1,0]
	s_nop 0
	v_rcp_f32_e32 v112, v112
	v_rcp_f32_e32 v113, v113
	s_nop 0
	v_pk_mul_f32 v[100:101], v[100:101], v[112:113]
	v_pk_mul_f32 v[112:113], v[136:137], v[108:109] op_sel_hi:[1,0]
	v_or_b32_e32 v109, 48, v133
	v_pk_mul_f32 v[102:103], v[102:103], v[112:113]
	v_cvt_pk_bf16_f32 v106, v100, v101
	v_pk_mul_f32 v[112:113], v[102:103], s[6:7] op_sel_hi:[1,0]
	v_mad_i64_i32 v[100:101], s[0:1], v109, s81, v[128:129]
	v_exp_f32_e32 v112, v112
	v_exp_f32_e32 v113, v113
	s_nop 0
	v_pk_add_f32 v[112:113], v[112:113], 1.0 op_sel_hi:[1,0]
	s_nop 0
	v_rcp_f32_e32 v112, v112
	v_rcp_f32_e32 v113, v113
	s_nop 0
	v_pk_mul_f32 v[102:103], v[102:103], v[112:113]
	s_nop 0
	v_cvt_pk_bf16_f32 v107, v102, v103
	v_lshl_add_u64 v[102:103], v[100:101], 0, v[66:67]
	ds_bpermute_b32 v100, v153, v152
	v_add_u32_e32 v101, 0x80, v133
	global_store_dwordx4 v[102:103], v[104:107], off
	s_waitcnt lgkmcnt(0)
; __device__ __forceinline__ unsigned cvt_pk_bf16(float lo, float hi) { f32x2_t v = {lo, hi}; bf16x2_t b = __builtin_convertvector(v, bf16x2_t); return __builtin_bit_cast(unsigned, b); }
; __device__ __forceinline__ float fast_rcp(float x) { return __builtin_amdgcn_rcpf(x); }
;     template <int KIND>
;     __device__ __forceinline__ void run(const f32x4 (&acc)[2][2][4][2], const Unit& u, int wr, int wc, int fr, int fq) const {
;     ...
;                 for (int m = 0; m < 4; ++m) { const int row = row0 + ai * HALF + m * 16; const float a = __shfl(ai ? sa_hi : sa_lo, 16 * m + fr);
;                     const f32x4 f0 = __builtin_convertvector(__builtin_bit_cast(i32x4, acc[ai][bj][m][0]), f32x4), f1 = __builtin_convertvector(__builtin_bit_cast(i32x4, acc[ai][bj][m][1]), f32x4);
;                     f32x2_t v[4] = {(f32x2_t){f0[0], f0[1]}, (f32x2_t){f0[2], f0[3]}, (f32x2_t){f1[0], f1[1]}, (f32x2_t){f1[2], f1[3]}};
; #pragma unroll
;                     for (int j = 0; j < 4; ++j) {
;                         v[j] = v[j] * (sc2[j] * (f32x2_t){a, a});
;                         if (KIND == 0 || KIND == 1 || KIND == 3) {
;                             const f32x2_t e = v[j] * (f32x2_t){-LOG2E, -LOG2E};
;                             const f32x2_t dn = (f32x2_t){__builtin_amdgcn_exp2f(e[0]), __builtin_amdgcn_exp2f(e[1])} + (f32x2_t){1.0f, 1.0f};
;                             const f32x2_t sg = (f32x2_t){fast_rcp(dn[0]), fast_rcp(dn[1])};
;                             if (KIND == 0) v[j] = v[j] * sg;
;                             else if (KIND == 3) v[j] = (v[j] * sg) * aux2[j];
;                             else { const f32x2_t f = __builtin_elementwise_fma((f32x2_t){1.0f, 1.0f} - aux2[j], sg, aux2[j]);
;                                 v[j] = (f32x2_t){fmaxf(__logf(f[0]), -60.0f), fmaxf(__logf(f[1]), -60.0f)}; }
;                         }
;                     }
;                     u32x4 w; w.x = cvt_pk_bf16(v[0][0], v[0][1]); w.y = cvt_pk_bf16(v[1][0], v[1][1]); w.z = cvt_pk_bf16(v[2][0], v[2][1]); w.w = cvt_pk_bf16(v[3][0], v[3][1]);
;                     *(u32x4*)(O + (size_t)row * NPROJ + col0 + bj * HALF) = w; }
	s_nop 0
	v_pk_mul_f32 v[104:105], v[150:151], v[100:101] op_sel_hi:[1,0]
	s_nop 0
	v_pk_mul_f32 v[96:97], v[96:97], v[104:105]
	s_nop 0
	v_pk_mul_f32 v[104:105], v[96:97], s[6:7] op_sel_hi:[1,0]
	s_nop 0
	v_exp_f32_e32 v104, v104
	v_exp_f32_e32 v105, v105
	s_nop 0
	v_pk_add_f32 v[104:105], v[104:105], 1.0 op_sel_hi:[1,0]
	s_nop 0
	v_rcp_f32_e32 v104, v104
	v_rcp_f32_e32 v105, v105
	s_nop 0
	v_pk_mul_f32 v[96:97], v[96:97], v[104:105]
	v_pk_mul_f32 v[104:105], v[148:149], v[100:101] op_sel_hi:[1,0]
	v_cvt_pk_bf16_f32 v96, v96, v97
	v_pk_mul_f32 v[98:99], v[98:99], v[104:105]
	s_nop 0
	v_pk_mul_f32 v[104:105], v[98:99], s[6:7] op_sel_hi:[1,0]
	s_nop 0
	v_exp_f32_e32 v104, v104
	v_exp_f32_e32 v105, v105
	s_nop 0
	v_pk_add_f32 v[104:105], v[104:105], 1.0 op_sel_hi:[1,0]
	s_nop 0
	v_rcp_f32_e32 v104, v104
	v_rcp_f32_e32 v105, v105
	s_nop 0
	v_pk_mul_f32 v[98:99], v[98:99], v[104:105]
	v_pk_mul_f32 v[104:105], v[138:139], v[100:101] op_sel_hi:[1,0]
	v_cvt_pk_bf16_f32 v97, v98, v99
	v_pk_mul_f32 v[92:93], v[92:93], v[104:105]
	s_nop 0
	v_pk_mul_f32 v[104:105], v[92:93], s[6:7] op_sel_hi:[1,0]
	s_nop 0
	v_exp_f32_e32 v104, v104
	v_exp_f32_e32 v105, v105
	s_nop 0
	v_pk_add_f32 v[104:105], v[104:105], 1.0 op_sel_hi:[1,0]
	s_nop 0
	v_rcp_f32_e32 v104, v104
	v_rcp_f32_e32 v105, v105
	s_nop 0
	v_pk_mul_f32 v[92:93], v[92:93], v[104:105]
	v_pk_mul_f32 v[104:105], v[136:137], v[100:101] op_sel_hi:[1,0]
	v_cvt_pk_bf16_f32 v98, v92, v93
	v_pk_mul_f32 v[94:95], v[94:95], v[104:105]
	v_mad_i64_i32 v[92:93], s[0:1], v101, s81, v[128:129]
	v_pk_mul_f32 v[104:105], v[94:95], s[6:7] op_sel_hi:[1,0]
	s_nop 0
	v_exp_f32_e32 v104, v104
	v_exp_f32_e32 v105, v105
	s_nop 0
	v_pk_add_f32 v[104:105], v[104:105], 1.0 op_sel_hi:[1,0]
	s_nop 0
	v_rcp_f32_e32 v104, v104
	v_rcp_f32_e32 v105, v105
	s_nop 0
	v_pk_mul_f32 v[94:95], v[94:95], v[104:105]
	s_nop 0
	v_cvt_pk_bf16_f32 v99, v94, v95
	v_lshl_add_u64 v[94:95], v[92:93], 0, v[66:67]
	ds_bpermute_b32 v92, v153, v152 offset:64
	global_store_dwordx4 v[94:95], v[96:99], off
	s_waitcnt lgkmcnt(0)
	s_nop 0
	v_pk_mul_f32 v[96:97], v[150:151], v[92:93] op_sel_hi:[1,0]
	s_nop 0
	v_pk_mul_f32 v[88:89], v[88:89], v[96:97]
	s_nop 0
	v_pk_mul_f32 v[96:97], v[88:89], s[6:7] op_sel_hi:[1,0]
	s_nop 0
	v_exp_f32_e32 v96, v96
	v_exp_f32_e32 v97, v97
	s_nop 0
	v_pk_add_f32 v[96:97], v[96:97], 1.0 op_sel_hi:[1,0]
	s_nop 0
	v_rcp_f32_e32 v96, v96
	v_rcp_f32_e32 v97, v97
	s_nop 0
	v_pk_mul_f32 v[88:89], v[88:89], v[96:97]
	v_pk_mul_f32 v[96:97], v[148:149], v[92:93] op_sel_hi:[1,0]
	v_cvt_pk_bf16_f32 v88, v88, v89
	v_pk_mul_f32 v[90:91], v[90:91], v[96:97]
	s_nop 0
	v_pk_mul_f32 v[96:97], v[90:91], s[6:7] op_sel_hi:[1,0]
	s_nop 0
	v_exp_f32_e32 v96, v96
	v_exp_f32_e32 v97, v97
	s_nop 0
	v_pk_add_f32 v[96:97], v[96:97], 1.0 op_sel_hi:[1,0]
	s_nop 0
	v_rcp_f32_e32 v96, v96
	v_rcp_f32_e32 v97, v97
	s_nop 0
	v_pk_mul_f32 v[90:91], v[90:91], v[96:97]
	v_pk_mul_f32 v[96:97], v[138:139], v[92:93] op_sel_hi:[1,0]
	v_cvt_pk_bf16_f32 v89, v90, v91
	v_pk_mul_f32 v[84:85], v[84:85], v[96:97]
	s_nop 0
	v_pk_mul_f32 v[96:97], v[84:85], s[6:7] op_sel_hi:[1,0]
	s_nop 0
	v_exp_f32_e32 v96, v96
	v_exp_f32_e32 v97, v97
	s_nop 0
	v_pk_add_f32 v[96:97], v[96:97], 1.0 op_sel_hi:[1,0]
	s_nop 0
	v_rcp_f32_e32 v96, v96
	v_rcp_f32_e32 v97, v97
	s_nop 0
	v_pk_mul_f32 v[84:85], v[84:85], v[96:97]
	v_pk_mul_f32 v[96:97], v[136:137], v[92:93] op_sel_hi:[1,0]
	v_add_u32_e32 v93, 0x90, v133
	v_pk_mul_f32 v[86:87], v[86:87], v[96:97]
	v_cvt_pk_bf16_f32 v90, v84, v85
	v_pk_mul_f32 v[96:97], v[86:87], s[6:7] op_sel_hi:[1,0]
	v_mad_i64_i32 v[84:85], s[0:1], v93, s81, v[128:129]
	v_exp_f32_e32 v96, v96
	v_exp_f32_e32 v97, v97
	s_nop 0
	v_pk_add_f32 v[96:97], v[96:97], 1.0 op_sel_hi:[1,0]
	s_nop 0
	v_rcp_f32_e32 v96, v96
	v_rcp_f32_e32 v97, v97
	s_nop 0
	v_pk_mul_f32 v[86:87], v[86:87], v[96:97]
	s_nop 0
	v_cvt_pk_bf16_f32 v91, v86, v87
	v_lshl_add_u64 v[86:87], v[84:85], 0, v[66:67]
	ds_bpermute_b32 v84, v153, v152 offset:128
	global_store_dwordx4 v[86:87], v[88:91], off
	s_waitcnt lgkmcnt(0)
	s_nop 0
	v_pk_mul_f32 v[88:89], v[150:151], v[84:85] op_sel_hi:[1,0]
	s_nop 0
	v_pk_mul_f32 v[80:81], v[80:81], v[88:89]
	s_nop 0
	v_pk_mul_f32 v[88:89], v[80:81], s[6:7] op_sel_hi:[1,0]
	s_nop 0
	v_exp_f32_e32 v88, v88
	v_exp_f32_e32 v89, v89
	s_nop 0
	v_pk_add_f32 v[88:89], v[88:89], 1.0 op_sel_hi:[1,0]
	s_nop 0
	v_rcp_f32_e32 v88, v88
	v_rcp_f32_e32 v89, v89
	s_nop 0
	v_pk_mul_f32 v[80:81], v[80:81], v[88:89]
	v_pk_mul_f32 v[88:89], v[148:149], v[84:85] op_sel_hi:[1,0]
	v_cvt_pk_bf16_f32 v80, v80, v81
	v_pk_mul_f32 v[82:83], v[82:83], v[88:89]
	s_nop 0
	v_pk_mul_f32 v[88:89], v[82:83], s[6:7] op_sel_hi:[1,0]
	s_nop 0
	v_exp_f32_e32 v88, v88
	v_exp_f32_e32 v89, v89
	s_nop 0
	v_pk_add_f32 v[88:89], v[88:89], 1.0 op_sel_hi:[1,0]
	s_nop 0
	v_rcp_f32_e32 v88, v88
	v_rcp_f32_e32 v89, v89
	s_nop 0
	v_pk_mul_f32 v[82:83], v[82:83], v[88:89]
	v_pk_mul_f32 v[88:89], v[138:139], v[84:85] op_sel_hi:[1,0]
	v_cvt_pk_bf16_f32 v81, v82, v83
	v_pk_mul_f32 v[76:77], v[76:77], v[88:89]
	s_nop 0
	v_pk_mul_f32 v[88:89], v[76:77], s[6:7] op_sel_hi:[1,0]
	s_nop 0
	v_exp_f32_e32 v88, v88
	v_exp_f32_e32 v89, v89
	s_nop 0
	v_pk_add_f32 v[88:89], v[88:89], 1.0 op_sel_hi:[1,0]
	s_nop 0
	v_rcp_f32_e32 v88, v88
	v_rcp_f32_e32 v89, v89
	s_nop 0
	v_pk_mul_f32 v[76:77], v[76:77], v[88:89]
	v_pk_mul_f32 v[88:89], v[136:137], v[84:85] op_sel_hi:[1,0]
	v_add_u32_e32 v85, 0xa0, v133
	v_pk_mul_f32 v[78:79], v[78:79], v[88:89]
	v_cvt_pk_bf16_f32 v82, v76, v77
	v_pk_mul_f32 v[88:89], v[78:79], s[6:7] op_sel_hi:[1,0]
	v_mad_i64_i32 v[76:77], s[0:1], v85, s81, v[128:129]
	v_exp_f32_e32 v88, v88
	v_exp_f32_e32 v89, v89
	s_nop 0
	v_pk_add_f32 v[88:89], v[88:89], 1.0 op_sel_hi:[1,0]
	s_nop 0
	v_rcp_f32_e32 v88, v88
	v_rcp_f32_e32 v89, v89
	s_nop 0
	v_pk_mul_f32 v[78:79], v[78:79], v[88:89]
	s_nop 0
	v_cvt_pk_bf16_f32 v83, v78, v79
	v_lshl_add_u64 v[78:79], v[76:77], 0, v[66:67]
	ds_bpermute_b32 v76, v153, v152 offset:192
	global_store_dwordx4 v[78:79], v[80:83], off
	s_waitcnt lgkmcnt(0)
; __device__ __forceinline__ unsigned cvt_pk_bf16(float lo, float hi) { f32x2_t v = {lo, hi}; bf16x2_t b = __builtin_convertvector(v, bf16x2_t); return __builtin_bit_cast(unsigned, b); }
; __device__ __forceinline__ float fast_rcp(float x) { return __builtin_amdgcn_rcpf(x); }
;     template <int KIND>
;     __device__ __forceinline__ void run(const f32x4 (&acc)[2][2][4][2], const Unit& u, int wr, int wc, int fr, int fq) const {
;     ...
;                 for (int m = 0; m < 4; ++m) { const int row = row0 + ai * HALF + m * 16; const float a = __shfl(ai ? sa_hi : sa_lo, 16 * m + fr);
;                     const f32x4 f0 = __builtin_convertvector(__builtin_bit_cast(i32x4, acc[ai][bj][m][0]), f32x4), f1 = __builtin_convertvector(__builtin_bit_cast(i32x4, acc[ai][bj][m][1]), f32x4);
;                     f32x2_t v[4] = {(f32x2_t){f0[0], f0[1]}, (f32x2_t){f0[2], f0[3]}, (f32x2_t){f1[0], f1[1]}, (f32x2_t){f1[2], f1[3]}};
; #pragma unroll
;                     for (int j = 0; j < 4; ++j) {
;                         v[j] = v[j] * (sc2[j] * (f32x2_t){a, a});
;                         if (KIND == 0 || KIND == 1 || KIND == 3) {
;                             const f32x2_t e = v[j] * (f32x2_t){-LOG2E, -LOG2E};
;                             const f32x2_t dn = (f32x2_t){__builtin_amdgcn_exp2f(e[0]), __builtin_amdgcn_exp2f(e[1])} + (f32x2_t){1.0f, 1.0f};
;                             const f32x2_t sg = (f32x2_t){fast_rcp(dn[0]), fast_rcp(dn[1])};
;                             if (KIND == 0) v[j] = v[j] * sg;
;                             else if (KIND == 3) v[j] = (v[j] * sg) * aux2[j];
;                             else { const f32x2_t f = __builtin_elementwise_fma((f32x2_t){1.0f, 1.0f} - aux2[j], sg, aux2[j]);
;                                 v[j] = (f32x2_t){fmaxf(__logf(f[0]), -60.0f), fmaxf(__logf(f[1]), -60.0f)}; }
;                         }
;                     }
;                     u32x4 w; w.x = cvt_pk_bf16(v[0][0], v[0][1]); w.y = cvt_pk_bf16(v[1][0], v[1][1]); w.z = cvt_pk_bf16(v[2][0], v[2][1]); w.w = cvt_pk_bf16(v[3][0], v[3][1]);
;                     *(u32x4*)(O + (size_t)row * NPROJ + col0 + bj * HALF) = w; }
	s_nop 0
	v_pk_mul_f32 v[80:81], v[150:151], v[76:77] op_sel_hi:[1,0]
	s_nop 0
	v_pk_mul_f32 v[72:73], v[72:73], v[80:81]
	s_nop 0
	v_pk_mul_f32 v[80:81], v[72:73], s[6:7] op_sel_hi:[1,0]
	s_nop 0
	v_exp_f32_e32 v80, v80
	v_exp_f32_e32 v81, v81
	s_nop 0
	v_pk_add_f32 v[80:81], v[80:81], 1.0 op_sel_hi:[1,0]
	s_nop 0
	v_rcp_f32_e32 v80, v80
	v_rcp_f32_e32 v81, v81
	s_nop 0
	v_pk_mul_f32 v[72:73], v[72:73], v[80:81]
	v_pk_mul_f32 v[80:81], v[148:149], v[76:77] op_sel_hi:[1,0]
	s_nop 0
	v_pk_mul_f32 v[74:75], v[74:75], v[80:81]
	s_nop 0
	v_pk_mul_f32 v[80:81], v[74:75], s[6:7] op_sel_hi:[1,0]
	s_nop 0
	v_exp_f32_e32 v80, v80
	v_exp_f32_e32 v81, v81
	s_nop 0
	v_pk_add_f32 v[80:81], v[80:81], 1.0 op_sel_hi:[1,0]
	s_nop 0
	v_rcp_f32_e32 v80, v80
	v_rcp_f32_e32 v81, v81
	s_nop 0
	v_pk_mul_f32 v[74:75], v[74:75], v[80:81]
	v_pk_mul_f32 v[80:81], v[138:139], v[76:77] op_sel_hi:[1,0]
	s_nop 0
	v_pk_mul_f32 v[68:69], v[68:69], v[80:81]
	s_nop 0
	v_pk_mul_f32 v[80:81], v[68:69], s[6:7] op_sel_hi:[1,0]
	s_nop 0
	v_exp_f32_e32 v80, v80
	v_exp_f32_e32 v81, v81
	s_nop 0
	v_pk_add_f32 v[80:81], v[80:81], 1.0 op_sel_hi:[1,0]
	s_nop 0
	v_rcp_f32_e32 v80, v80
	v_rcp_f32_e32 v81, v81
	s_nop 0
	v_pk_mul_f32 v[80:81], v[68:69], v[80:81]
	v_pk_mul_f32 v[68:69], v[136:137], v[76:77] op_sel_hi:[1,0]
	v_add_u32_e32 v77, 0xb0, v133
	v_pk_mul_f32 v[68:69], v[70:71], v[68:69]
	v_mad_i64_i32 v[150:151], s[0:1], v77, s81, 0
	v_pk_mul_f32 v[70:71], v[68:69], s[6:7] op_sel_hi:[1,0]
	s_nop 0
	v_exp_f32_e32 v70, v70
	v_exp_f32_e32 v71, v71
	s_nop 0
	v_pk_add_f32 v[70:71], v[70:71], 1.0 op_sel_hi:[1,0]
	s_nop 0
	v_rcp_f32_e32 v70, v70
	v_rcp_f32_e32 v71, v71
	s_nop 0
	v_pk_mul_f32 v[82:83], v[68:69], v[70:71]
	v_cvt_pk_bf16_f32 v68, v72, v73
	v_mad_i64_i32 v[72:73], s[0:1], v77, s81, v[128:129]
	v_cvt_pk_bf16_f32 v69, v74, v75
	v_cvt_pk_bf16_f32 v70, v80, v81
	v_cvt_pk_bf16_f32 v71, v82, v83
	v_lshl_add_u64 v[72:73], v[72:73], 0, v[66:67]
	global_store_dwordx4 v[72:73], v[68:71], off
	s_nop 1
	s_waitcnt vmcnt(8)
	v_mov_b32_e32 v80, v236
	v_mov_b32_e32 v81, v237
	v_mov_b32_e32 v82, v238
	v_mov_b32_e32 v83, v239
	v_mov_b32_e32 v68, v240
	v_mov_b32_e32 v69, v241
	v_mov_b32_e32 v70, v242
	v_mov_b32_e32 v71, v243
	v_pk_mul_f32 v[74:75], v[68:69], s[2:3] op_sel_hi:[1,0]
	v_pk_mul_f32 v[72:73], v[70:71], s[2:3] op_sel_hi:[1,0]
	v_pk_mul_f32 v[70:71], v[80:81], s[2:3] op_sel_hi:[1,0]
	v_pk_mul_f32 v[80:81], v[132:133], v[74:75] op_sel_hi:[0,1]
	v_pk_mul_f32 v[62:63], v[62:63], v[80:81]
	v_pk_mul_f32 v[68:69], v[82:83], s[2:3] op_sel_hi:[1,0]
	v_pk_mul_f32 v[80:81], v[62:63], s[6:7] op_sel_hi:[1,0]
	s_nop 0
	v_exp_f32_e32 v80, v80
	v_exp_f32_e32 v81, v81
	s_nop 0
	v_pk_add_f32 v[80:81], v[80:81], 1.0 op_sel_hi:[1,0]
	s_nop 0
	v_rcp_f32_e32 v80, v80
	v_rcp_f32_e32 v81, v81
	s_nop 0
	v_pk_mul_f32 v[62:63], v[62:63], v[80:81]
	v_pk_mul_f32 v[80:81], v[132:133], v[72:73] op_sel_hi:[0,1]
	v_pk_mul_f32 v[64:65], v[64:65], v[80:81]
	s_nop 0
	v_pk_mul_f32 v[80:81], v[64:65], s[6:7] op_sel_hi:[1,0]
	s_nop 0
	v_exp_f32_e32 v80, v80
	v_exp_f32_e32 v81, v81
	s_nop 0
	v_pk_add_f32 v[80:81], v[80:81], 1.0 op_sel_hi:[1,0]
	s_nop 0
	v_rcp_f32_e32 v80, v80
	v_rcp_f32_e32 v81, v81
	s_nop 0
	v_pk_mul_f32 v[64:65], v[64:65], v[80:81]
	v_pk_mul_f32 v[80:81], v[132:133], v[70:71] op_sel_hi:[0,1]
	v_pk_mul_f32 v[58:59], v[58:59], v[80:81]
	s_nop 0
	v_pk_mul_f32 v[80:81], v[58:59], s[6:7] op_sel_hi:[1,0]
	s_nop 0
	v_exp_f32_e32 v80, v80
	v_exp_f32_e32 v81, v81
	s_nop 0
	v_pk_add_f32 v[80:81], v[80:81], 1.0 op_sel_hi:[1,0]
	s_nop 0
	v_rcp_f32_e32 v80, v80
	v_rcp_f32_e32 v81, v81
	s_nop 0
	v_pk_mul_f32 v[80:81], v[58:59], v[80:81]
	v_pk_mul_f32 v[58:59], v[132:133], v[68:69] op_sel_hi:[0,1]
	v_pk_mul_f32 v[58:59], v[60:61], v[58:59]
	s_nop 0
	v_pk_mul_f32 v[60:61], v[58:59], s[6:7] op_sel_hi:[1,0]
	s_nop 0
	v_exp_f32_e32 v60, v60
	v_exp_f32_e32 v61, v61
	s_nop 0
	v_pk_add_f32 v[60:61], v[60:61], 1.0 op_sel_hi:[1,0]
	s_nop 0
	v_rcp_f32_e32 v60, v60
	v_rcp_f32_e32 v61, v61
	s_nop 0
	v_pk_mul_f32 v[82:83], v[58:59], v[60:61]
	v_cvt_pk_bf16_f32 v58, v62, v63
	v_cvt_pk_bf16_f32 v59, v64, v65
	v_cvt_pk_bf16_f32 v60, v80, v81
	v_cvt_pk_bf16_f32 v61, v82, v83
	global_store_dwordx4 v[126:127], v[58:61], off offset:256
	s_nop 1
	v_pk_mul_f32 v[58:59], v[124:125], v[74:75] op_sel_hi:[0,1]
	v_pk_mul_f32 v[54:55], v[54:55], v[58:59]
	s_nop 0
	v_pk_mul_f32 v[58:59], v[54:55], s[6:7] op_sel_hi:[1,0]
	s_nop 0
	v_exp_f32_e32 v58, v58
	v_exp_f32_e32 v59, v59
	s_nop 0
	v_pk_add_f32 v[58:59], v[58:59], 1.0 op_sel_hi:[1,0]
	s_nop 0
	v_rcp_f32_e32 v58, v58
	v_rcp_f32_e32 v59, v59
	s_nop 0
	v_pk_mul_f32 v[54:55], v[54:55], v[58:59]
	v_pk_mul_f32 v[58:59], v[124:125], v[72:73] op_sel_hi:[0,1]
	v_pk_mul_f32 v[56:57], v[56:57], v[58:59]
	s_nop 0
	v_pk_mul_f32 v[58:59], v[56:57], s[6:7] op_sel_hi:[1,0]
	s_nop 0
	v_exp_f32_e32 v58, v58
	v_exp_f32_e32 v59, v59
	s_nop 0
	v_pk_add_f32 v[58:59], v[58:59], 1.0 op_sel_hi:[1,0]
	s_nop 0
	v_rcp_f32_e32 v58, v58
	v_rcp_f32_e32 v59, v59
	s_nop 0
	v_pk_mul_f32 v[56:57], v[56:57], v[58:59]
	v_pk_mul_f32 v[58:59], v[124:125], v[70:71] op_sel_hi:[0,1]
	v_pk_mul_f32 v[50:51], v[50:51], v[58:59]
	s_nop 0
	v_pk_mul_f32 v[58:59], v[50:51], s[6:7] op_sel_hi:[1,0]
	s_nop 0
	v_exp_f32_e32 v58, v58
	v_exp_f32_e32 v59, v59
	s_nop 0
	v_pk_add_f32 v[58:59], v[58:59], 1.0 op_sel_hi:[1,0]
	s_nop 0
	v_rcp_f32_e32 v58, v58
	v_rcp_f32_e32 v59, v59
	s_nop 0
	v_pk_mul_f32 v[58:59], v[50:51], v[58:59]
	v_pk_mul_f32 v[50:51], v[124:125], v[68:69] op_sel_hi:[0,1]
	v_pk_mul_f32 v[50:51], v[52:53], v[50:51]
	s_nop 0
	v_pk_mul_f32 v[52:53], v[50:51], s[6:7] op_sel_hi:[1,0]
	s_nop 0
	v_exp_f32_e32 v52, v52
	v_exp_f32_e32 v53, v53
; __device__ __forceinline__ unsigned cvt_pk_bf16(float lo, float hi) { f32x2_t v = {lo, hi}; bf16x2_t b = __builtin_convertvector(v, bf16x2_t); return __builtin_bit_cast(unsigned, b); }
; __device__ __forceinline__ float fast_rcp(float x) { return __builtin_amdgcn_rcpf(x); }
;     template <int KIND>
;     __device__ __forceinline__ void run(const f32x4 (&acc)[2][2][4][2], const Unit& u, int wr, int wc, int fr, int fq) const {
;     ...
;                 for (int m = 0; m < 4; ++m) { const int row = row0 + ai * HALF + m * 16; const float a = __shfl(ai ? sa_hi : sa_lo, 16 * m + fr);
;                     const f32x4 f0 = __builtin_convertvector(__builtin_bit_cast(i32x4, acc[ai][bj][m][0]), f32x4), f1 = __builtin_convertvector(__builtin_bit_cast(i32x4, acc[ai][bj][m][1]), f32x4);
;                     f32x2_t v[4] = {(f32x2_t){f0[0], f0[1]}, (f32x2_t){f0[2], f0[3]}, (f32x2_t){f1[0], f1[1]}, (f32x2_t){f1[2], f1[3]}};
; #pragma unroll
;                     for (int j = 0; j < 4; ++j) {
;                         v[j] = v[j] * (sc2[j] * (f32x2_t){a, a});
;                         if (KIND == 0 || KIND == 1 || KIND == 3) {
;                             const f32x2_t e = v[j] * (f32x2_t){-LOG2E, -LOG2E};
;                             const f32x2_t dn = (f32x2_t){__builtin_amdgcn_exp2f(e[0]), __builtin_amdgcn_exp2f(e[1])} + (f32x2_t){1.0f, 1.0f};
;                             const f32x2_t sg = (f32x2_t){fast_rcp(dn[0]), fast_rcp(dn[1])};
;                             if (KIND == 0) v[j] = v[j] * sg;
;                             else if (KIND == 3) v[j] = (v[j] * sg) * aux2[j];
;                             else { const f32x2_t f = __builtin_elementwise_fma((f32x2_t){1.0f, 1.0f} - aux2[j], sg, aux2[j]);
;                                 v[j] = (f32x2_t){fmaxf(__logf(f[0]), -60.0f), fmaxf(__logf(f[1]), -60.0f)}; }
;                         }
;                     }
;                     u32x4 w; w.x = cvt_pk_bf16(v[0][0], v[0][1]); w.y = cvt_pk_bf16(v[1][0], v[1][1]); w.z = cvt_pk_bf16(v[2][0], v[2][1]); w.w = cvt_pk_bf16(v[3][0], v[3][1]);
;                     *(u32x4*)(O + (size_t)row * NPROJ + col0 + bj * HALF) = w; }
	s_nop 0
	v_pk_add_f32 v[52:53], v[52:53], 1.0 op_sel_hi:[1,0]
	s_nop 0
	v_rcp_f32_e32 v52, v52
	v_rcp_f32_e32 v53, v53
	s_nop 0
	v_pk_mul_f32 v[60:61], v[50:51], v[52:53]
	v_cvt_pk_bf16_f32 v50, v54, v55
	v_cvt_pk_bf16_f32 v51, v56, v57
	v_cvt_pk_bf16_f32 v52, v58, v59
	v_cvt_pk_bf16_f32 v53, v60, v61
	global_store_dwordx4 v[118:119], v[50:53], off offset:256
	s_nop 1
	v_pk_mul_f32 v[50:51], v[116:117], v[74:75] op_sel_hi:[0,1]
	v_pk_mul_f32 v[46:47], v[46:47], v[50:51]
	s_nop 0
	v_pk_mul_f32 v[50:51], v[46:47], s[6:7] op_sel_hi:[1,0]
	s_nop 0
	v_exp_f32_e32 v50, v50
	v_exp_f32_e32 v51, v51
	s_nop 0
	v_pk_add_f32 v[50:51], v[50:51], 1.0 op_sel_hi:[1,0]
	s_nop 0
	v_rcp_f32_e32 v50, v50
	v_rcp_f32_e32 v51, v51
	s_nop 0
	v_pk_mul_f32 v[46:47], v[46:47], v[50:51]
	v_pk_mul_f32 v[50:51], v[116:117], v[72:73] op_sel_hi:[0,1]
	v_pk_mul_f32 v[48:49], v[48:49], v[50:51]
	s_nop 0
	v_pk_mul_f32 v[50:51], v[48:49], s[6:7] op_sel_hi:[1,0]
	s_nop 0
	v_exp_f32_e32 v50, v50
	v_exp_f32_e32 v51, v51
	s_nop 0
	v_pk_add_f32 v[50:51], v[50:51], 1.0 op_sel_hi:[1,0]
	s_nop 0
	v_rcp_f32_e32 v50, v50
	v_rcp_f32_e32 v51, v51
	s_nop 0
	v_pk_mul_f32 v[48:49], v[48:49], v[50:51]
	v_pk_mul_f32 v[50:51], v[116:117], v[70:71] op_sel_hi:[0,1]
	v_pk_mul_f32 v[42:43], v[42:43], v[50:51]
	s_nop 0
	v_pk_mul_f32 v[50:51], v[42:43], s[6:7] op_sel_hi:[1,0]
	s_nop 0
	v_exp_f32_e32 v50, v50
	v_exp_f32_e32 v51, v51
	s_nop 0
	v_pk_add_f32 v[50:51], v[50:51], 1.0 op_sel_hi:[1,0]
	s_nop 0
	v_rcp_f32_e32 v50, v50
	v_rcp_f32_e32 v51, v51
	s_nop 0
	v_pk_mul_f32 v[50:51], v[42:43], v[50:51]
	v_pk_mul_f32 v[42:43], v[116:117], v[68:69] op_sel_hi:[0,1]
	v_pk_mul_f32 v[42:43], v[44:45], v[42:43]
	s_nop 0
	v_pk_mul_f32 v[44:45], v[42:43], s[6:7] op_sel_hi:[1,0]
	s_nop 0
	v_exp_f32_e32 v44, v44
	v_exp_f32_e32 v45, v45
	s_nop 0
	v_pk_add_f32 v[44:45], v[44:45], 1.0 op_sel_hi:[1,0]
	s_nop 0
	v_rcp_f32_e32 v44, v44
	v_rcp_f32_e32 v45, v45
	s_nop 0
	v_pk_mul_f32 v[52:53], v[42:43], v[44:45]
	v_cvt_pk_bf16_f32 v42, v46, v47
	v_cvt_pk_bf16_f32 v43, v48, v49
	v_cvt_pk_bf16_f32 v44, v50, v51
	v_cvt_pk_bf16_f32 v45, v52, v53
	global_store_dwordx4 v[110:111], v[42:45], off offset:256
	s_nop 1
	v_pk_mul_f32 v[42:43], v[108:109], v[74:75] op_sel_hi:[0,1]
	v_pk_mul_f32 v[38:39], v[38:39], v[42:43]
	s_nop 0
	v_pk_mul_f32 v[42:43], v[38:39], s[6:7] op_sel_hi:[1,0]
	s_nop 0
	v_exp_f32_e32 v42, v42
	v_exp_f32_e32 v43, v43
	s_nop 0
	v_pk_add_f32 v[42:43], v[42:43], 1.0 op_sel_hi:[1,0]
	s_nop 0
	v_rcp_f32_e32 v42, v42
	v_rcp_f32_e32 v43, v43
	s_nop 0
	v_pk_mul_f32 v[38:39], v[38:39], v[42:43]
	v_pk_mul_f32 v[42:43], v[108:109], v[72:73] op_sel_hi:[0,1]
	v_pk_mul_f32 v[40:41], v[40:41], v[42:43]
	s_nop 0
	v_pk_mul_f32 v[42:43], v[40:41], s[6:7] op_sel_hi:[1,0]
	s_nop 0
	v_exp_f32_e32 v42, v42
	v_exp_f32_e32 v43, v43
	s_nop 0
	v_pk_add_f32 v[42:43], v[42:43], 1.0 op_sel_hi:[1,0]
	s_nop 0
	v_rcp_f32_e32 v42, v42
	v_rcp_f32_e32 v43, v43
	s_nop 0
	v_pk_mul_f32 v[40:41], v[40:41], v[42:43]
	v_pk_mul_f32 v[42:43], v[108:109], v[70:71] op_sel_hi:[0,1]
	v_pk_mul_f32 v[34:35], v[34:35], v[42:43]
	s_nop 0
	v_pk_mul_f32 v[42:43], v[34:35], s[6:7] op_sel_hi:[1,0]
	s_nop 0
	v_exp_f32_e32 v42, v42
	v_exp_f32_e32 v43, v43
	s_nop 0
	v_pk_add_f32 v[42:43], v[42:43], 1.0 op_sel_hi:[1,0]
	s_nop 0
	v_rcp_f32_e32 v42, v42
	v_rcp_f32_e32 v43, v43
	s_nop 0
	v_pk_mul_f32 v[42:43], v[34:35], v[42:43]
	v_pk_mul_f32 v[34:35], v[108:109], v[68:69] op_sel_hi:[0,1]
	v_pk_mul_f32 v[34:35], v[36:37], v[34:35]
	s_nop 0
	v_pk_mul_f32 v[36:37], v[34:35], s[6:7] op_sel_hi:[1,0]
	s_nop 0
	v_exp_f32_e32 v36, v36
	v_exp_f32_e32 v37, v37
	s_nop 0
	v_pk_add_f32 v[36:37], v[36:37], 1.0 op_sel_hi:[1,0]
	s_nop 0
	v_rcp_f32_e32 v36, v36
	v_rcp_f32_e32 v37, v37
	s_nop 0
	v_pk_mul_f32 v[44:45], v[34:35], v[36:37]
	v_cvt_pk_bf16_f32 v34, v38, v39
	v_cvt_pk_bf16_f32 v35, v40, v41
	v_cvt_pk_bf16_f32 v36, v42, v43
	v_cvt_pk_bf16_f32 v37, v44, v45
	global_store_dwordx4 v[102:103], v[34:37], off offset:256
	s_nop 1
	v_pk_mul_f32 v[34:35], v[100:101], v[74:75] op_sel_hi:[0,1]
	v_pk_mul_f32 v[30:31], v[30:31], v[34:35]
	s_nop 0
	v_pk_mul_f32 v[34:35], v[30:31], s[6:7] op_sel_hi:[1,0]
	s_nop 0
	v_exp_f32_e32 v34, v34
	v_exp_f32_e32 v35, v35
	s_nop 0
	v_pk_add_f32 v[34:35], v[34:35], 1.0 op_sel_hi:[1,0]
	s_nop 0
	v_rcp_f32_e32 v34, v34
	v_rcp_f32_e32 v35, v35
	s_nop 0
	v_pk_mul_f32 v[30:31], v[30:31], v[34:35]
	v_pk_mul_f32 v[34:35], v[100:101], v[72:73] op_sel_hi:[0,1]
	v_pk_mul_f32 v[32:33], v[32:33], v[34:35]
	s_nop 0
	v_pk_mul_f32 v[34:35], v[32:33], s[6:7] op_sel_hi:[1,0]
	s_nop 0
	v_exp_f32_e32 v34, v34
	v_exp_f32_e32 v35, v35
	s_nop 0
	v_pk_add_f32 v[34:35], v[34:35], 1.0 op_sel_hi:[1,0]
	s_nop 0
	v_rcp_f32_e32 v34, v34
	v_rcp_f32_e32 v35, v35
	s_nop 0
	v_pk_mul_f32 v[32:33], v[32:33], v[34:35]
	v_pk_mul_f32 v[34:35], v[100:101], v[70:71] op_sel_hi:[0,1]
	v_pk_mul_f32 v[26:27], v[26:27], v[34:35]
	s_nop 0
	v_pk_mul_f32 v[34:35], v[26:27], s[6:7] op_sel_hi:[1,0]
	s_nop 0
	v_exp_f32_e32 v34, v34
	v_exp_f32_e32 v35, v35
	s_nop 0
	v_pk_add_f32 v[34:35], v[34:35], 1.0 op_sel_hi:[1,0]
	s_nop 0
	v_rcp_f32_e32 v34, v34
	v_rcp_f32_e32 v35, v35
	s_nop 0
	v_pk_mul_f32 v[34:35], v[26:27], v[34:35]
	v_pk_mul_f32 v[26:27], v[100:101], v[68:69] op_sel_hi:[0,1]
	v_pk_mul_f32 v[26:27], v[28:29], v[26:27]
	s_nop 0
	v_pk_mul_f32 v[28:29], v[26:27], s[6:7] op_sel_hi:[1,0]
	s_nop 0
	v_exp_f32_e32 v28, v28
	v_exp_f32_e32 v29, v29
	s_nop 0
; __device__ __forceinline__ unsigned cvt_pk_bf16(float lo, float hi) { f32x2_t v = {lo, hi}; bf16x2_t b = __builtin_convertvector(v, bf16x2_t); return __builtin_bit_cast(unsigned, b); }
; __device__ __forceinline__ float fast_rcp(float x) { return __builtin_amdgcn_rcpf(x); }
;     template <int KIND>
;     __device__ __forceinline__ void run(const f32x4 (&acc)[2][2][4][2], const Unit& u, int wr, int wc, int fr, int fq) const {
;     ...
;                 for (int m = 0; m < 4; ++m) { const int row = row0 + ai * HALF + m * 16; const float a = __shfl(ai ? sa_hi : sa_lo, 16 * m + fr);
;                     const f32x4 f0 = __builtin_convertvector(__builtin_bit_cast(i32x4, acc[ai][bj][m][0]), f32x4), f1 = __builtin_convertvector(__builtin_bit_cast(i32x4, acc[ai][bj][m][1]), f32x4);
;                     f32x2_t v[4] = {(f32x2_t){f0[0], f0[1]}, (f32x2_t){f0[2], f0[3]}, (f32x2_t){f1[0], f1[1]}, (f32x2_t){f1[2], f1[3]}};
; #pragma unroll
;                     for (int j = 0; j < 4; ++j) {
;                         v[j] = v[j] * (sc2[j] * (f32x2_t){a, a});
;                         if (KIND == 0 || KIND == 1 || KIND == 3) {
;                             const f32x2_t e = v[j] * (f32x2_t){-LOG2E, -LOG2E};
;                             const f32x2_t dn = (f32x2_t){__builtin_amdgcn_exp2f(e[0]), __builtin_amdgcn_exp2f(e[1])} + (f32x2_t){1.0f, 1.0f};
;                             const f32x2_t sg = (f32x2_t){fast_rcp(dn[0]), fast_rcp(dn[1])};
;                             if (KIND == 0) v[j] = v[j] * sg;
;                             else if (KIND == 3) v[j] = (v[j] * sg) * aux2[j];
;                             else { const f32x2_t f = __builtin_elementwise_fma((f32x2_t){1.0f, 1.0f} - aux2[j], sg, aux2[j]);
;                                 v[j] = (f32x2_t){fmaxf(__logf(f[0]), -60.0f), fmaxf(__logf(f[1]), -60.0f)}; }
;                         }
;                     }
;                     u32x4 w; w.x = cvt_pk_bf16(v[0][0], v[0][1]); w.y = cvt_pk_bf16(v[1][0], v[1][1]); w.z = cvt_pk_bf16(v[2][0], v[2][1]); w.w = cvt_pk_bf16(v[3][0], v[3][1]);
;                     *(u32x4*)(O + (size_t)row * NPROJ + col0 + bj * HALF) = w; }
	v_pk_add_f32 v[28:29], v[28:29], 1.0 op_sel_hi:[1,0]
	s_nop 0
	v_rcp_f32_e32 v28, v28
	v_rcp_f32_e32 v29, v29
	s_nop 0
	v_pk_mul_f32 v[36:37], v[26:27], v[28:29]
	v_cvt_pk_bf16_f32 v26, v30, v31
	v_cvt_pk_bf16_f32 v27, v32, v33
	v_cvt_pk_bf16_f32 v28, v34, v35
	v_cvt_pk_bf16_f32 v29, v36, v37
	global_store_dwordx4 v[94:95], v[26:29], off offset:256
	s_nop 1
	v_pk_mul_f32 v[26:27], v[92:93], v[74:75] op_sel_hi:[0,1]
	v_pk_mul_f32 v[22:23], v[22:23], v[26:27]
	s_nop 0
	v_pk_mul_f32 v[26:27], v[22:23], s[6:7] op_sel_hi:[1,0]
	s_nop 0
	v_exp_f32_e32 v26, v26
	v_exp_f32_e32 v27, v27
	s_nop 0
	v_pk_add_f32 v[26:27], v[26:27], 1.0 op_sel_hi:[1,0]
	s_nop 0
	v_rcp_f32_e32 v26, v26
	v_rcp_f32_e32 v27, v27
	s_nop 0
	v_pk_mul_f32 v[22:23], v[22:23], v[26:27]
	v_pk_mul_f32 v[26:27], v[92:93], v[72:73] op_sel_hi:[0,1]
	v_pk_mul_f32 v[24:25], v[24:25], v[26:27]
	s_nop 0
	v_pk_mul_f32 v[26:27], v[24:25], s[6:7] op_sel_hi:[1,0]
	s_nop 0
	v_exp_f32_e32 v26, v26
	v_exp_f32_e32 v27, v27
	s_nop 0
	v_pk_add_f32 v[26:27], v[26:27], 1.0 op_sel_hi:[1,0]
	s_nop 0
	v_rcp_f32_e32 v26, v26
	v_rcp_f32_e32 v27, v27
	s_nop 0
	v_pk_mul_f32 v[24:25], v[24:25], v[26:27]
	v_pk_mul_f32 v[26:27], v[92:93], v[70:71] op_sel_hi:[0,1]
	v_pk_mul_f32 v[18:19], v[18:19], v[26:27]
	s_nop 0
	v_pk_mul_f32 v[26:27], v[18:19], s[6:7] op_sel_hi:[1,0]
	s_nop 0
	v_exp_f32_e32 v26, v26
	v_exp_f32_e32 v27, v27
	s_nop 0
	v_pk_add_f32 v[26:27], v[26:27], 1.0 op_sel_hi:[1,0]
	s_nop 0
	v_rcp_f32_e32 v26, v26
	v_rcp_f32_e32 v27, v27
	s_nop 0
	v_pk_mul_f32 v[26:27], v[18:19], v[26:27]
	v_pk_mul_f32 v[18:19], v[92:93], v[68:69] op_sel_hi:[0,1]
	v_pk_mul_f32 v[18:19], v[20:21], v[18:19]
	s_nop 0
	v_pk_mul_f32 v[20:21], v[18:19], s[6:7] op_sel_hi:[1,0]
	s_nop 0
	v_exp_f32_e32 v20, v20
	v_exp_f32_e32 v21, v21
	s_nop 0
	v_pk_add_f32 v[20:21], v[20:21], 1.0 op_sel_hi:[1,0]
	s_nop 0
	v_rcp_f32_e32 v20, v20
	v_rcp_f32_e32 v21, v21
	s_nop 0
	v_pk_mul_f32 v[28:29], v[18:19], v[20:21]
	v_cvt_pk_bf16_f32 v18, v22, v23
	v_cvt_pk_bf16_f32 v19, v24, v25
	v_cvt_pk_bf16_f32 v20, v26, v27
	v_cvt_pk_bf16_f32 v21, v28, v29
	global_store_dwordx4 v[86:87], v[18:21], off offset:256
	s_nop 1
	v_pk_mul_f32 v[18:19], v[84:85], v[74:75] op_sel_hi:[0,1]
	v_pk_mul_f32 v[14:15], v[14:15], v[18:19]
	s_nop 0
	v_pk_mul_f32 v[18:19], v[14:15], s[6:7] op_sel_hi:[1,0]
	s_nop 0
	v_exp_f32_e32 v18, v18
	v_exp_f32_e32 v19, v19
	s_nop 0
	v_pk_add_f32 v[18:19], v[18:19], 1.0 op_sel_hi:[1,0]
	s_nop 0
	v_rcp_f32_e32 v18, v18
	v_rcp_f32_e32 v19, v19
	s_nop 0
	v_pk_mul_f32 v[14:15], v[14:15], v[18:19]
	v_pk_mul_f32 v[18:19], v[84:85], v[72:73] op_sel_hi:[0,1]
	v_pk_mul_f32 v[16:17], v[16:17], v[18:19]
	s_nop 0
	v_pk_mul_f32 v[18:19], v[16:17], s[6:7] op_sel_hi:[1,0]
	s_nop 0
	v_exp_f32_e32 v18, v18
	v_exp_f32_e32 v19, v19
	s_nop 0
	v_pk_add_f32 v[18:19], v[18:19], 1.0 op_sel_hi:[1,0]
	s_nop 0
	v_rcp_f32_e32 v18, v18
	v_rcp_f32_e32 v19, v19
	s_nop 0
	v_pk_mul_f32 v[16:17], v[16:17], v[18:19]
	v_pk_mul_f32 v[18:19], v[84:85], v[70:71] op_sel_hi:[0,1]
	v_pk_mul_f32 v[10:11], v[10:11], v[18:19]
	s_nop 0
	v_pk_mul_f32 v[18:19], v[10:11], s[6:7] op_sel_hi:[1,0]
	s_nop 0
	v_exp_f32_e32 v18, v18
	v_exp_f32_e32 v19, v19
	s_nop 0
	v_pk_add_f32 v[18:19], v[18:19], 1.0 op_sel_hi:[1,0]
	s_nop 0
	v_rcp_f32_e32 v18, v18
	v_rcp_f32_e32 v19, v19
	s_nop 0
	v_pk_mul_f32 v[18:19], v[10:11], v[18:19]
	v_pk_mul_f32 v[10:11], v[84:85], v[68:69] op_sel_hi:[0,1]
	v_pk_mul_f32 v[10:11], v[12:13], v[10:11]
	s_nop 0
	v_pk_mul_f32 v[12:13], v[10:11], s[6:7] op_sel_hi:[1,0]
	s_nop 0
	v_exp_f32_e32 v12, v12
	v_exp_f32_e32 v13, v13
	s_nop 0
	v_pk_add_f32 v[12:13], v[12:13], 1.0 op_sel_hi:[1,0]
	s_nop 0
	v_rcp_f32_e32 v12, v12
	v_rcp_f32_e32 v13, v13
	s_nop 0
	v_pk_mul_f32 v[20:21], v[10:11], v[12:13]
	v_cvt_pk_bf16_f32 v10, v14, v15
	v_cvt_pk_bf16_f32 v11, v16, v17
	v_cvt_pk_bf16_f32 v12, v18, v19
	v_cvt_pk_bf16_f32 v13, v20, v21
	global_store_dwordx4 v[78:79], v[10:13], off offset:256
	s_nop 1
	v_pk_mul_f32 v[10:11], v[76:77], v[74:75] op_sel_hi:[0,1]
	v_pk_mul_f32 v[6:7], v[6:7], v[10:11]
	s_nop 0
	v_pk_mul_f32 v[10:11], v[6:7], s[6:7] op_sel_hi:[1,0]
	s_nop 0
	v_exp_f32_e32 v10, v10
	v_exp_f32_e32 v11, v11
	s_nop 0
	v_pk_add_f32 v[10:11], v[10:11], 1.0 op_sel_hi:[1,0]
	s_nop 0
	v_rcp_f32_e32 v10, v10
	v_rcp_f32_e32 v11, v11
	s_nop 0
	v_pk_mul_f32 v[136:137], v[6:7], v[10:11]
	v_pk_mul_f32 v[6:7], v[76:77], v[72:73] op_sel_hi:[0,1]
	v_pk_mul_f32 v[6:7], v[8:9], v[6:7]
	s_nop 0
	v_pk_mul_f32 v[8:9], v[6:7], s[6:7] op_sel_hi:[1,0]
	s_nop 0
	v_exp_f32_e32 v8, v8
	v_exp_f32_e32 v9, v9
	s_nop 0
	v_pk_add_f32 v[8:9], v[8:9], 1.0 op_sel_hi:[1,0]
	s_nop 0
	v_rcp_f32_e32 v8, v8
	v_rcp_f32_e32 v9, v9
	s_nop 0
	v_pk_mul_f32 v[138:139], v[6:7], v[8:9]
	v_pk_mul_f32 v[6:7], v[76:77], v[70:71] op_sel_hi:[0,1]
	v_pk_mul_f32 v[2:3], v[2:3], v[6:7]
	s_nop 0
	v_pk_mul_f32 v[6:7], v[2:3], s[6:7] op_sel_hi:[1,0]
	s_nop 0
	v_exp_f32_e32 v6, v6
	v_exp_f32_e32 v7, v7
	s_nop 0
	v_pk_add_f32 v[6:7], v[6:7], 1.0 op_sel_hi:[1,0]
	s_nop 0
	v_rcp_f32_e32 v6, v6
	v_rcp_f32_e32 v7, v7
	s_nop 0
	v_pk_mul_f32 v[132:133], v[2:3], v[6:7]
	v_pk_mul_f32 v[2:3], v[76:77], v[68:69] op_sel_hi:[0,1]
	v_pk_mul_f32 v[2:3], v[4:5], v[2:3]
	s_nop 0
	v_pk_mul_f32 v[4:5], v[2:3], s[6:7] op_sel_hi:[1,0]
	s_nop 0
	v_exp_f32_e32 v4, v4
	v_exp_f32_e32 v5, v5
	s_nop 0
	v_pk_add_f32 v[4:5], v[4:5], 1.0 op_sel_hi:[1,0]
	s_nop 0
	v_rcp_f32_e32 v4, v4
	v_rcp_f32_e32 v5, v5
	s_nop 0
	v_pk_mul_f32 v[134:135], v[2:3], v[4:5]
